# no accumulator zeroing pass: peeled first K-iteration per tile whose k=0 MFMAs take C=0
# baseline (speedup 1.0000x reference)
.LBB0_130:
	s_add_u32 s38, s38, 0x80
	s_addc_u32 s39, s39, 0
	s_add_u32 s56, s88, 0x100
	s_addc_u32 s57, s89, 0
	s_mov_b32 s44, 0
	s_add_i32 s74, s44, 2
	s_add_u32 s75, s38, 0x80
	s_addc_u32 s45, s39, 0
	s_add_i32 s94, 0, 0x10000
	s_cmp_eq_u32 s11, s44
	s_cselect_b32 s45, s93, s45
	s_cselect_b32 s44, s92, s75
	s_cselect_b32 s89, s99, s57
	s_cselect_b32 s88, s98, s56
	s_add_i32 s75, 0, 0x14000
	v_add_u32_e32 v142, s94, v242
	v_add_u32_e32 v158, s100, v242
	ds_read_b128 v[130:133], v142
	ds_read_b128 v[134:137], v142 offset:1024
	ds_read_b128 v[138:141], v142 offset:2048
	ds_read_b128 v[142:145], v142 offset:3072
	ds_read_b128 v[146:149], v158
	ds_read_b128 v[150:153], v158 offset:1024
	ds_read_b128 v[154:157], v158 offset:2048
	ds_read_b128 v[158:161], v158 offset:3072
	v_lshl_add_u64 v[212:213], s[38:39], 0, v[176:177]
	s_add_i32 m0, s3, 0xc000
	ds_read_b128 v[180:183], v243
	ds_read_b128 v[184:187], v243 offset:1024
	ds_read_b128 v[188:191], v243 offset:2048
	ds_read_b128 v[192:195], v243 offset:3072
	ds_read_b128 v[196:199], v243 offset:4096
	ds_read_b128 v[200:203], v243 offset:5120
	ds_read_b128 v[204:207], v243 offset:6144
	ds_read_b128 v[208:211], v243 offset:7168
	global_load_lds_dwordx4 v[212:213], off
	v_lshl_add_u64 v[212:213], s[38:39], 0, v[178:179]
	s_add_i32 m0, s3, 0xe000
	s_nop 0
	global_load_lds_dwordx4 v[212:213], off
	s_waitcnt vmcnt(8)
	s_waitcnt lgkmcnt(0)
	s_barrier
	s_setprio 1
	s_waitcnt lgkmcnt(0)
	v_mfma_f32_16x16x32_bf16 v[126:129], v[130:133], v[180:183], 0
	v_mfma_f32_16x16x32_bf16 v[122:125], v[138:141], v[180:183], 0
	v_mfma_f32_16x16x32_bf16 v[110:113], v[130:133], v[188:191], 0
	v_mfma_f32_16x16x32_bf16 v[106:109], v[138:141], v[188:191], 0
	v_mfma_f32_16x16x32_bf16 v[94:97], v[130:133], v[196:199], 0
	v_mfma_f32_16x16x32_bf16 v[90:93], v[138:141], v[196:199], 0
	v_mfma_f32_16x16x32_bf16 v[78:81], v[130:133], v[204:207], 0
	v_mfma_f32_16x16x32_bf16 v[74:77], v[138:141], v[204:207], 0
	v_mfma_f32_16x16x32_bf16 v[126:129], v[134:137], v[184:187], v[126:129]
	v_mfma_f32_16x16x32_bf16 v[122:125], v[142:145], v[184:187], v[122:125]
	v_mfma_f32_16x16x32_bf16 v[110:113], v[134:137], v[192:195], v[110:113]
	v_mfma_f32_16x16x32_bf16 v[106:109], v[142:145], v[192:195], v[106:109]
	v_mfma_f32_16x16x32_bf16 v[94:97], v[134:137], v[200:203], v[94:97]
	v_mfma_f32_16x16x32_bf16 v[90:93], v[142:145], v[200:203], v[90:93]
	v_mfma_f32_16x16x32_bf16 v[78:81], v[134:137], v[208:211], v[78:81]
	v_mfma_f32_16x16x32_bf16 v[74:77], v[142:145], v[208:211], v[74:77]
	s_setprio 0
	s_setprio 1
	v_mfma_f32_16x16x32_bf16 v[118:121], v[146:149], v[180:183], 0
	v_mfma_f32_16x16x32_bf16 v[114:117], v[154:157], v[180:183], 0
	v_mfma_f32_16x16x32_bf16 v[102:105], v[146:149], v[188:191], 0
	v_mfma_f32_16x16x32_bf16 v[98:101], v[154:157], v[188:191], 0
	v_mfma_f32_16x16x32_bf16 v[86:89], v[146:149], v[196:199], 0
	v_mfma_f32_16x16x32_bf16 v[82:85], v[154:157], v[196:199], 0
	v_mfma_f32_16x16x32_bf16 v[70:73], v[146:149], v[204:207], 0
	v_mfma_f32_16x16x32_bf16 v[66:69], v[154:157], v[204:207], 0
	v_mfma_f32_16x16x32_bf16 v[118:121], v[150:153], v[184:187], v[118:121]
	v_mfma_f32_16x16x32_bf16 v[114:117], v[158:161], v[184:187], v[114:117]
	v_mfma_f32_16x16x32_bf16 v[102:105], v[150:153], v[192:195], v[102:105]
	v_mfma_f32_16x16x32_bf16 v[98:101], v[158:161], v[192:195], v[98:101]
	v_mfma_f32_16x16x32_bf16 v[86:89], v[150:153], v[200:203], v[86:89]
	v_mfma_f32_16x16x32_bf16 v[82:85], v[158:161], v[200:203], v[82:85]
	v_mfma_f32_16x16x32_bf16 v[70:73], v[150:153], v[208:211], v[70:73]
	v_mfma_f32_16x16x32_bf16 v[66:69], v[158:161], v[208:211], v[66:69]
	s_setprio 0
	s_barrier
	s_add_i32 s94, s94, s77
	v_lshl_add_u64 v[212:213], s[88:89], 0, v[166:167]
	s_mov_b32 m0, s94
	ds_read_b128 v[180:183], v243 offset:16384
	ds_read_b128 v[184:187], v243 offset:17408
	ds_read_b128 v[188:191], v243 offset:18432
	ds_read_b128 v[192:195], v243 offset:19456
	ds_read_b128 v[196:199], v243 offset:20480
	ds_read_b128 v[200:203], v243 offset:21504
	ds_read_b128 v[204:207], v243 offset:22528
	ds_read_b128 v[208:211], v243 offset:23552
	global_load_lds_dwordx4 v[212:213], off
	s_add_i32 m0, s94, 0x2000
	v_lshl_add_u64 v[214:215], s[88:89], 0, v[170:171]
	s_add_u32 s88, s88, s96
	s_addc_u32 s89, s89, 0
	s_add_i32 s75, s75, s77
	global_load_lds_dwordx4 v[214:215], off
	v_lshl_add_u64 v[216:217], s[88:89], 0, v[166:167]
	s_mov_b32 m0, s75
	v_lshl_add_u64 v[218:219], s[88:89], 0, v[170:171]
	global_load_lds_dwordx4 v[216:217], off
	s_add_i32 m0, s75, 0x2000
	v_lshl_add_u64 v[220:221], s[44:45], 0, v[164:165]
	global_load_lds_dwordx4 v[218:219], off
	s_mov_b32 m0, s3
	v_lshl_add_u64 v[222:223], s[44:45], 0, v[168:169]
	global_load_lds_dwordx4 v[220:221], off
	s_mov_b32 m0, s78
	s_nop 0
	global_load_lds_dwordx4 v[222:223], off
	s_waitcnt vmcnt(8)
	s_waitcnt lgkmcnt(0)
	s_barrier
	s_setprio 1
	s_waitcnt lgkmcnt(0)
	v_mfma_f32_16x16x32_bf16 v[62:65], v[130:133], v[180:183], 0
	v_mfma_f32_16x16x32_bf16 v[58:61], v[138:141], v[180:183], 0
	v_mfma_f32_16x16x32_bf16 v[46:49], v[130:133], v[188:191], 0
	v_mfma_f32_16x16x32_bf16 v[42:45], v[138:141], v[188:191], 0
	v_mfma_f32_16x16x32_bf16 v[30:33], v[130:133], v[196:199], 0
	v_mfma_f32_16x16x32_bf16 v[26:29], v[138:141], v[196:199], 0
	v_mfma_f32_16x16x32_bf16 v[14:17], v[130:133], v[204:207], 0
	v_mfma_f32_16x16x32_bf16 v[10:13], v[138:141], v[204:207], 0
	v_mfma_f32_16x16x32_bf16 v[62:65], v[134:137], v[184:187], v[62:65]
	v_mfma_f32_16x16x32_bf16 v[58:61], v[142:145], v[184:187], v[58:61]
	v_mfma_f32_16x16x32_bf16 v[46:49], v[134:137], v[192:195], v[46:49]
	v_mfma_f32_16x16x32_bf16 v[42:45], v[142:145], v[192:195], v[42:45]
	v_mfma_f32_16x16x32_bf16 v[30:33], v[134:137], v[200:203], v[30:33]
	v_mfma_f32_16x16x32_bf16 v[26:29], v[142:145], v[200:203], v[26:29]
	v_mfma_f32_16x16x32_bf16 v[14:17], v[134:137], v[208:211], v[14:17]
	v_mfma_f32_16x16x32_bf16 v[10:13], v[142:145], v[208:211], v[10:13]
	s_setprio 0
	s_setprio 1
	v_mfma_f32_16x16x32_bf16 v[54:57], v[146:149], v[180:183], 0
	v_mfma_f32_16x16x32_bf16 v[50:53], v[154:157], v[180:183], 0
	v_mfma_f32_16x16x32_bf16 v[38:41], v[146:149], v[188:191], 0
	v_mfma_f32_16x16x32_bf16 v[34:37], v[154:157], v[188:191], 0
	v_mfma_f32_16x16x32_bf16 v[22:25], v[146:149], v[196:199], 0
	v_mfma_f32_16x16x32_bf16 v[18:21], v[154:157], v[196:199], 0
	v_mfma_f32_16x16x32_bf16 v[6:9], v[146:149], v[204:207], 0
	v_mfma_f32_16x16x32_bf16 v[2:5], v[154:157], v[204:207], 0
	v_mfma_f32_16x16x32_bf16 v[54:57], v[150:153], v[184:187], v[54:57]
	v_mfma_f32_16x16x32_bf16 v[50:53], v[158:161], v[184:187], v[50:53]
	v_mfma_f32_16x16x32_bf16 v[38:41], v[150:153], v[192:195], v[38:41]
	v_mfma_f32_16x16x32_bf16 v[34:37], v[158:161], v[192:195], v[34:37]
	v_mfma_f32_16x16x32_bf16 v[22:25], v[150:153], v[200:203], v[22:25]
	v_mfma_f32_16x16x32_bf16 v[18:21], v[158:161], v[200:203], v[18:21]
	v_mfma_f32_16x16x32_bf16 v[6:9], v[150:153], v[208:211], v[6:9]
	v_mfma_f32_16x16x32_bf16 v[2:5], v[158:161], v[208:211], v[2:5]
	s_setprio 0
	s_barrier
	s_add_i32 s75, 0, 0x18000
	s_add_i32 s88, 0, 0x1c000
	v_add_u32_e32 v142, s75, v242
	s_add_i32 vcc_lo, s100, 0x8000
	v_add_u32_e32 v158, vcc_lo, v242
	ds_read_b128 v[130:133], v142
	ds_read_b128 v[134:137], v142 offset:1024
	ds_read_b128 v[138:141], v142 offset:2048
	ds_read_b128 v[142:145], v142 offset:3072
	ds_read_b128 v[146:149], v158
	ds_read_b128 v[150:153], v158 offset:1024
	ds_read_b128 v[154:157], v158 offset:2048
	ds_read_b128 v[158:161], v158 offset:3072
	s_add_u32 s44, s44, s96
	s_addc_u32 s45, s45, 0
	s_mov_b32 m0, s9
	v_lshl_add_u64 v[224:225], s[44:45], 0, v[164:165]
	ds_read_b128 v[180:183], v243 offset:32768
	ds_read_b128 v[184:187], v243 offset:33792
	ds_read_b128 v[188:191], v243 offset:34816
	ds_read_b128 v[192:195], v243 offset:35840
	ds_read_b128 v[196:199], v243 offset:36864
	ds_read_b128 v[200:203], v243 offset:37888
	ds_read_b128 v[204:207], v243 offset:38912
	ds_read_b128 v[208:211], v243 offset:39936
	global_load_lds_dwordx4 v[224:225], off
	v_lshl_add_u64 v[224:225], s[44:45], 0, v[168:169]
	s_mov_b32 m0, s86
	s_nop 0
	global_load_lds_dwordx4 v[224:225], off
	s_waitcnt vmcnt(8)
	s_waitcnt lgkmcnt(0)
	s_barrier
	s_setprio 1
	s_waitcnt lgkmcnt(0)
	v_mfma_f32_16x16x32_bf16 v[126:129], v[130:133], v[180:183], v[126:129]
	v_mfma_f32_16x16x32_bf16 v[122:125], v[138:141], v[180:183], v[122:125]
	v_mfma_f32_16x16x32_bf16 v[110:113], v[130:133], v[188:191], v[110:113]
	v_mfma_f32_16x16x32_bf16 v[106:109], v[138:141], v[188:191], v[106:109]
	v_mfma_f32_16x16x32_bf16 v[94:97], v[130:133], v[196:199], v[94:97]
	v_mfma_f32_16x16x32_bf16 v[90:93], v[138:141], v[196:199], v[90:93]
	v_mfma_f32_16x16x32_bf16 v[78:81], v[130:133], v[204:207], v[78:81]
	v_mfma_f32_16x16x32_bf16 v[74:77], v[138:141], v[204:207], v[74:77]
	v_mfma_f32_16x16x32_bf16 v[126:129], v[134:137], v[184:187], v[126:129]
	v_mfma_f32_16x16x32_bf16 v[122:125], v[142:145], v[184:187], v[122:125]
	v_mfma_f32_16x16x32_bf16 v[110:113], v[134:137], v[192:195], v[110:113]
	v_mfma_f32_16x16x32_bf16 v[106:109], v[142:145], v[192:195], v[106:109]
	v_mfma_f32_16x16x32_bf16 v[94:97], v[134:137], v[200:203], v[94:97]
	v_mfma_f32_16x16x32_bf16 v[90:93], v[142:145], v[200:203], v[90:93]
	v_mfma_f32_16x16x32_bf16 v[78:81], v[134:137], v[208:211], v[78:81]
	v_mfma_f32_16x16x32_bf16 v[74:77], v[142:145], v[208:211], v[74:77]
	s_setprio 0
	s_setprio 1
	v_mfma_f32_16x16x32_bf16 v[118:121], v[146:149], v[180:183], v[118:121]
	v_mfma_f32_16x16x32_bf16 v[114:117], v[154:157], v[180:183], v[114:117]
	v_mfma_f32_16x16x32_bf16 v[102:105], v[146:149], v[188:191], v[102:105]
	v_mfma_f32_16x16x32_bf16 v[98:101], v[154:157], v[188:191], v[98:101]
	v_mfma_f32_16x16x32_bf16 v[86:89], v[146:149], v[196:199], v[86:89]
	v_mfma_f32_16x16x32_bf16 v[82:85], v[154:157], v[196:199], v[82:85]
	v_mfma_f32_16x16x32_bf16 v[70:73], v[146:149], v[204:207], v[70:73]
	v_mfma_f32_16x16x32_bf16 v[66:69], v[154:157], v[204:207], v[66:69]
	v_mfma_f32_16x16x32_bf16 v[118:121], v[150:153], v[184:187], v[118:121]
	v_mfma_f32_16x16x32_bf16 v[114:117], v[158:161], v[184:187], v[114:117]
	v_mfma_f32_16x16x32_bf16 v[102:105], v[150:153], v[192:195], v[102:105]
	v_mfma_f32_16x16x32_bf16 v[98:101], v[158:161], v[192:195], v[98:101]
	v_mfma_f32_16x16x32_bf16 v[86:89], v[150:153], v[200:203], v[86:89]
	v_mfma_f32_16x16x32_bf16 v[82:85], v[158:161], v[200:203], v[82:85]
	v_mfma_f32_16x16x32_bf16 v[70:73], v[150:153], v[208:211], v[70:73]
	v_mfma_f32_16x16x32_bf16 v[66:69], v[158:161], v[208:211], v[66:69]
	s_setprio 0
	s_barrier
	s_add_i32 s44, s75, s77
	v_lshl_add_u64 v[212:213], v[212:213], 0, s[4:5]
	s_mov_b32 m0, s44
	ds_read_b128 v[180:183], v243 offset:49152
	ds_read_b128 v[184:187], v243 offset:50176
	ds_read_b128 v[188:191], v243 offset:51200
	ds_read_b128 v[192:195], v243 offset:52224
	ds_read_b128 v[196:199], v243 offset:53248
	ds_read_b128 v[200:203], v243 offset:54272
	ds_read_b128 v[204:207], v243 offset:55296
	ds_read_b128 v[208:211], v243 offset:56320
	global_load_lds_dwordx4 v[212:213], off
	v_lshl_add_u64 v[212:213], v[214:215], 0, s[4:5]
	s_add_i32 m0, s44, 0x2000
	s_add_i32 s44, s88, s77
	global_load_lds_dwordx4 v[212:213], off
	v_lshl_add_u64 v[212:213], v[216:217], 0, s[4:5]
	s_mov_b32 m0, s44
	s_nop 0
	global_load_lds_dwordx4 v[212:213], off
	v_lshl_add_u64 v[212:213], v[218:219], 0, s[4:5]
	s_add_i32 m0, s44, 0x2000
	s_nop 0
	global_load_lds_dwordx4 v[212:213], off
	v_lshl_add_u64 v[212:213], v[220:221], 0, s[4:5]
	s_mov_b32 m0, s80
	s_nop 0
	global_load_lds_dwordx4 v[212:213], off
	v_lshl_add_u64 v[212:213], v[222:223], 0, s[4:5]
	s_mov_b32 m0, s84
	s_nop 0
	global_load_lds_dwordx4 v[212:213], off
	s_waitcnt vmcnt(8)
	s_waitcnt lgkmcnt(0)
	s_barrier
	s_setprio 1
	s_waitcnt lgkmcnt(0)
	v_mfma_f32_16x16x32_bf16 v[62:65], v[130:133], v[180:183], v[62:65]
	v_mfma_f32_16x16x32_bf16 v[58:61], v[138:141], v[180:183], v[58:61]
	v_mfma_f32_16x16x32_bf16 v[46:49], v[130:133], v[188:191], v[46:49]
	v_mfma_f32_16x16x32_bf16 v[42:45], v[138:141], v[188:191], v[42:45]
	v_mfma_f32_16x16x32_bf16 v[30:33], v[130:133], v[196:199], v[30:33]
	v_mfma_f32_16x16x32_bf16 v[26:29], v[138:141], v[196:199], v[26:29]
	v_mfma_f32_16x16x32_bf16 v[14:17], v[130:133], v[204:207], v[14:17]
	v_mfma_f32_16x16x32_bf16 v[10:13], v[138:141], v[204:207], v[10:13]
	v_mfma_f32_16x16x32_bf16 v[62:65], v[134:137], v[184:187], v[62:65]
	v_mfma_f32_16x16x32_bf16 v[58:61], v[142:145], v[184:187], v[58:61]
	v_mfma_f32_16x16x32_bf16 v[46:49], v[134:137], v[192:195], v[46:49]
	v_mfma_f32_16x16x32_bf16 v[42:45], v[142:145], v[192:195], v[42:45]
	v_mfma_f32_16x16x32_bf16 v[30:33], v[134:137], v[200:203], v[30:33]
	v_mfma_f32_16x16x32_bf16 v[26:29], v[142:145], v[200:203], v[26:29]
	v_mfma_f32_16x16x32_bf16 v[14:17], v[134:137], v[208:211], v[14:17]
	v_mfma_f32_16x16x32_bf16 v[10:13], v[142:145], v[208:211], v[10:13]
	s_setprio 0
	s_setprio 1
	v_mfma_f32_16x16x32_bf16 v[54:57], v[146:149], v[180:183], v[54:57]
	v_mfma_f32_16x16x32_bf16 v[50:53], v[154:157], v[180:183], v[50:53]
	v_mfma_f32_16x16x32_bf16 v[38:41], v[146:149], v[188:191], v[38:41]
	v_mfma_f32_16x16x32_bf16 v[34:37], v[154:157], v[188:191], v[34:37]
	v_mfma_f32_16x16x32_bf16 v[22:25], v[146:149], v[196:199], v[22:25]
	v_mfma_f32_16x16x32_bf16 v[18:21], v[154:157], v[196:199], v[18:21]
	v_mfma_f32_16x16x32_bf16 v[6:9], v[146:149], v[204:207], v[6:9]
	v_mfma_f32_16x16x32_bf16 v[2:5], v[154:157], v[204:207], v[2:5]
	v_mfma_f32_16x16x32_bf16 v[54:57], v[150:153], v[184:187], v[54:57]
	v_mfma_f32_16x16x32_bf16 v[50:53], v[158:161], v[184:187], v[50:53]
	v_mfma_f32_16x16x32_bf16 v[38:41], v[150:153], v[192:195], v[38:41]
	v_mfma_f32_16x16x32_bf16 v[34:37], v[158:161], v[192:195], v[34:37]
	v_mfma_f32_16x16x32_bf16 v[22:25], v[150:153], v[200:203], v[22:25]
	v_mfma_f32_16x16x32_bf16 v[18:21], v[158:161], v[200:203], v[18:21]
	v_mfma_f32_16x16x32_bf16 v[6:9], v[150:153], v[208:211], v[6:9]
	v_mfma_f32_16x16x32_bf16 v[2:5], v[158:161], v[208:211], v[2:5]
	s_setprio 0
	s_barrier
	s_add_u32 s38, s38, 0x100
	s_addc_u32 s39, s39, 0
	s_add_u32 s56, s56, 0x100
	s_addc_u32 s57, s57, 0
	s_cmp_ge_u32 s74, s83
	s_mov_b32 s44, s74
	s_cbranch_scc0 .LBB0_131
	s_branch .Lk_done

.Lk_done:
	s_and_b64 vcc, exec, s[30:31]
	s_cbranch_vccz .LBB0_134
	s_barrier
